# v59 plus gather compaction: both selection-word loads of a 1024-candidate chunk issued together (prologue de-serialisation)
# speedup vs baseline: 1.0054x; 1.0001x over previous
; __device__ __forceinline__ void moba_gather(const bf16* __restrict__ Z, const bf16* __restrict__ ZT, const unsigned* __restrict__ SEL, bf16* __restrict__ PO, float* __restrict__ PLSE, unsigned* qctr, LAS unsigned char* lds) {
;     ...
;             if (tid == 0) *cntp = 0u;
;             asm volatile("s_waitcnt lgkmcnt(0)" ::: "memory"); __syncthreads();
; #pragma unroll
;             for (int sub = 0; sub < 2; ++sub) { const int t = base + sub * 512 + tid; int slot = -1;
;                 if (t < sb * 256) { const unsigned sel = SEL[(size_t)h * T_SEQ + t]; slot = ((sel & 0xffu) == (unsigned)n) ? 0 : ((((sel >> 8) & 0xffu) == (unsigned)n) ? 1 : ((((sel >> 16) & 0xffu) == (unsigned)n) ? 2 : -1)); }
;                 const unsigned long long bal = __ballot(slot >= 0); const int nb = __popcll(bal);
;                 unsigned wbase = 0u; if (lane == 0 && nb) wbase = __hip_atomic_fetch_add(cntp, (unsigned)nb, __ATOMIC_RELAXED, __HIP_MEMORY_SCOPE_WORKGROUP);
;                 wbase = __builtin_amdgcn_readfirstlane(wbase);
;                 if (slot >= 0) lst[wbase + __popcll(bal & ((1ull << lane) - 1ull))] = (unsigned)t | ((unsigned)slot << 16); }
.LBB0_1715:
	s_and_saveexec_b64 s[6:7], s[0:1]
	v_mov_b32_e32 v4, s68
	ds_write_b32 v4, v3
	s_or_b64 exec, exec, s[6:7]
	s_waitcnt lgkmcnt(0)
	v_add_u32_e32 v4, s46, v161
	v_cmp_gt_i32_e32 vcc, s47, v4
	v_mov_b32_e32 v5, -1
	s_waitcnt lgkmcnt(0)
	s_barrier
	s_and_saveexec_b64 s[6:7], vcc
	s_cbranch_execz .LBB0_1721
	v_ashrrev_i32_e32 v5, 31, v4
	v_lshl_add_u64 v[6:7], v[4:5], 2, s[30:31]
	global_load_dword v226, v[6:7], off offset:2048
	global_load_dword v6, v[6:7], off
	v_mov_b32_e32 v5, 0
	s_waitcnt vmcnt(0)
	v_cmp_ne_u32_sdwa s[36:37], v6, s40 src0_sel:BYTE_0 src1_sel:DWORD
	s_and_saveexec_b64 s[34:35], s[36:37]
	v_cmp_eq_u32_sdwa s[36:37], v6, s40 src0_sel:BYTE_2 src1_sel:DWORD
	v_cmp_ne_u32_sdwa vcc, v6, s40 src0_sel:BYTE_1 src1_sel:DWORD
	s_nop 0
	v_cndmask_b32_e64 v5, -1, 2, s[36:37]
	v_cndmask_b32_e32 v5, 1, v5, vcc
	s_or_b64 exec, exec, s[34:35]

; __device__ __forceinline__ void moba_gather(const bf16* __restrict__ Z, const bf16* __restrict__ ZT, const unsigned* __restrict__ SEL, bf16* __restrict__ PO, float* __restrict__ PLSE, unsigned* qctr, LAS unsigned char* lds) {
;     ...
;             for (int sub = 0; sub < 2; ++sub) { const int t = base + sub * 512 + tid; int slot = -1;
;                 if (t < sb * 256) { const unsigned sel = SEL[(size_t)h * T_SEQ + t]; slot = ((sel & 0xffu) == (unsigned)n) ? 0 : ((((sel >> 8) & 0xffu) == (unsigned)n) ? 1 : ((((sel >> 16) & 0xffu) == (unsigned)n) ? 2 : -1)); }
;                 const unsigned long long bal = __ballot(slot >= 0); const int nb = __popcll(bal);
;                 unsigned wbase = 0u; if (lane == 0 && nb) wbase = __hip_atomic_fetch_add(cntp, (unsigned)nb, __ATOMIC_RELAXED, __HIP_MEMORY_SCOPE_WORKGROUP);
;                 wbase = __builtin_amdgcn_readfirstlane(wbase);
;                 if (slot >= 0) lst[wbase + __popcll(bal & ((1ull << lane) - 1ull))] = (unsigned)t | ((unsigned)slot << 16); }
.LBB0_1727:
	s_or_b64 exec, exec, s[6:7]
	v_add_u32_e32 v4, 0x200, v4
	v_cmp_gt_i32_e32 vcc, s47, v4
	v_mov_b32_e32 v5, -1
	s_and_saveexec_b64 s[6:7], vcc
	s_cbranch_execz .LBB0_1731
	v_mov_b32_e32 v6, v226
	v_mov_b32_e32 v5, 0
	v_cmp_ne_u32_sdwa s[36:37], v6, s40 src0_sel:BYTE_0 src1_sel:DWORD
	s_and_saveexec_b64 s[34:35], s[36:37]
	v_cmp_eq_u32_sdwa s[36:37], v6, s40 src0_sel:BYTE_2 src1_sel:DWORD
	v_cmp_ne_u32_sdwa vcc, v6, s40 src0_sel:BYTE_1 src1_sel:DWORD
	s_nop 0
	v_cndmask_b32_e64 v5, -1, 2, s[36:37]
	v_cndmask_b32_e32 v5, 1, v5, vcc
	s_or_b64 exec, exec, s[34:35]
